# XCC-local barriers for attn->outproj, gateup->down, down->norm1 seams (+latent attention unit remap), early L1 invalidate in local barriers, PV operand loads de-serialized in attention loops
# speedup vs baseline: 1.0065x; 1.0065x over previous
.LBB0_1048:
	s_or_b64 exec, exec, s[8:9]
	buffer_inv sc1
	s_waitcnt vmcnt(0)
	v_readfirstlane_b32 s6, v4
	s_mov_b32 s7, s36
	s_nop 0
	v_add_u32_e32 v2, s6, v2
	s_add_i32 s6, s10, 0x11c0
	s_lshl_b64 s[6:7], s[6:7], 2
	s_add_u32 s8, s2, s6
	v_and_b32_e32 v4, 31, v2
	s_addc_u32 s9, s3, s7
	v_cmp_ne_u32_e32 vcc, 31, v4
	s_mov_b64 s[10:11], -1
	v_mov_b64_e32 v[4:5], s[8:9]
	s_and_saveexec_b64 s[6:7], vcc
	s_cbranch_execz .LBB0_1060
	global_load_dword v4, v3, s[8:9] sc1
	v_lshrrev_b32_e32 v2, 5, v2
	s_mov_b64 s[14:15], 0
	s_waitcnt vmcnt(0)
	v_cmp_eq_u32_e32 vcc, v4, v2
	s_and_saveexec_b64 s[12:13], vcc
	s_cbranch_execz .LBB0_1059
	s_add_u32 s10, s2, 0x200
	s_addc_u32 s11, s3, 0
	s_mov_b32 s20, 1
	s_mov_b64 s[2:3], 0
	s_branch .LBB0_1052

.LBB0_1062:
	s_or_b64 exec, exec, s[2:3]
	s_waitcnt vmcnt(0)
	s_waitcnt vmcnt(0)

.LBB0_2477:
	s_lshr_b32 s8, s69, 2
	s_and_b64 s[6:7], s[24:25], exec
	s_cselect_b32 s6, s8, s69
	s_and_b32 s18, s6, 7
	s_lshl_b64 s[6:7], s[40:41], 10
	s_add_u32 s6, s37, s6
	s_addc_u32 s7, s52, s7
	s_lshl_b32 s70, s18, 7
	s_add_u32 s6, s6, s70
	s_addc_u32 s7, s7, 0
	s_lshl_b64 s[8:9], s[40:41], 9
	s_add_u32 s8, s53, s8
	s_addc_u32 s9, s56, s9
	s_lshl_b32 s18, s18, 6
	s_add_u32 s8, s8, s18
	s_addc_u32 s9, s9, 0
	s_lshl_b64 s[42:43], s[4:5], 10
	s_add_u32 s18, s59, s42
	s_addc_u32 s19, s66, s43
	s_add_u32 s48, s18, s70
	v_mov_b32_e32 v197, v0
	s_addc_u32 s49, s19, 0
	s_lshl_b64 s[44:45], s[4:5], 6
	s_add_u32 s46, s57, s44
	v_ashrrev_i32_e32 v47, 1, v197
	v_bfi_b32 v4, s31, v47, v197
	s_addc_u32 s47, s58, s45
	v_ashrrev_i32_e32 v5, 31, v4
	s_add_u32 s4, s67, s42
	s_waitcnt vmcnt(0)
	v_lshlrev_b64 v[6:7], 10, v[4:5]
	v_lshlrev_b64 v[4:5], 9, v[4:5]
	v_ashrrev_i32_e32 v50, 3, v197
	s_addc_u32 s5, s68, s43
	v_lshl_add_u64 v[6:7], s[6:7], 0, v[6:7]
	v_and_b32_e32 v48, 32, v197
	v_mov_b32_e32 v49, v3
	v_lshl_add_u64 v[4:5], s[8:9], 0, v[4:5]
	v_and_b32_e32 v12, 7, v197
	v_ashrrev_i32_e32 v51, 31, v50
	s_add_u32 s50, s4, s70
	v_mov_b32_e32 v196, 0x7f7f7f7f
	v_lshl_add_u64 v[6:7], v[6:7], 0, v[48:49]
	v_lshl_add_u64 v[4:5], v[4:5], 0, v[48:49]
	v_lshlrev_b32_e32 v2, 4, v12
	v_lshlrev_b64 v[44:45], 10, v[50:51]
	s_addc_u32 s51, s5, 0
	global_load_dwordx4 v[120:123], v[6:7], off offset:16
	global_load_dwordx4 v[116:119], v[6:7], off
	global_load_dwordx4 v[112:115], v[6:7], off offset:80
	global_load_dwordx4 v[108:111], v[6:7], off offset:64
	global_load_dwordx4 v[104:107], v[4:5], off offset:16
	global_load_dwordx4 v[100:103], v[4:5], off
	v_or_b32_e32 v4, v44, v2
	v_mov_b32_e32 v5, v45
	v_lshl_add_u64 v[6:7], s[50:51], 0, v[4:5]
	v_lshl_add_u64 v[4:5], s[48:49], 0, v[4:5]
	global_load_dwordx4 v[8:11], v[6:7], off
	s_nop 0
	global_load_dwordx4 v[4:7], v[4:5], off
	v_lshlrev_b32_e32 v49, 4, v197
	s_movk_i32 s4, 0xff
	s_movk_i32 s6, 0x100
	v_bfe_u32 v55, v197, 2, 6
	v_and_b32_e32 v46, 48, v49
	v_cmp_lt_i32_e64 s[4:5], s4, v197
	v_cmp_gt_i32_e64 s[6:7], s6, v197
	s_and_saveexec_b64 s[8:9], s[6:7]
	s_cbranch_execz .LBB0_2479
	v_lshl_or_b32 v13, v55, 6, v46
	global_load_dwordx4 v[164:167], v13, s[46:47]

.LBB0_2494:
	s_or_b64 exec, exec, s[8:9]
	s_waitcnt lgkmcnt(9)
	v_mfma_scale_f32_32x32x64_f8f6f4 v[84:99], v[68:75], v[116:123], 0, v196, v196 op_sel_hi:[0,0,0]
	s_add_i32 s8, s46, 1
	s_cmp_lg_u32 s46, 2
	s_cselect_b32 s45, s8, 0
	s_addk_i32 s18, 0xe000
	s_cmp_lg_u32 s46, 0
	s_cselect_b32 s8, s18, 0x4000
	v_add_u32_e32 v2, s8, v201
	v_add_u32_e32 v212, s8, v203
	v_add_u32_e32 v213, s8, v204
	s_waitcnt lgkmcnt(8)
	v_mfma_scale_f32_32x32x64_f8f6f4 v[68:83], v[76:83], v[116:123], 0, v196, v196 op_sel_hi:[0,0,0]
	s_waitcnt lgkmcnt(5)
	v_mfma_scale_f32_32x32x64_f8f6f4 v[84:99], v[156:163], v[108:115], v[84:99], v196, v196 op_sel_hi:[0,0,0]
	s_waitcnt lgkmcnt(4)
	v_mfma_scale_f32_32x32x64_f8f6f4 v[68:83], v[148:155], v[108:115], v[68:83], v196, v196 op_sel_hi:[0,0,0]
	s_waitcnt lgkmcnt(1)
	v_mfma_scale_f32_32x32x64_f8f6f4 v[84:99], v[140:147], v[100:107], v[84:99], v196, v196 op_sel_hi:[0,0,0]
	v_add_u32_e32 v140, s8, v202
	s_waitcnt lgkmcnt(0)
	v_mfma_scale_f32_32x32x64_f8f6f4 v[68:83], v[132:139], v[100:107], v[68:83], v196, v196 op_sel_hi:[0,0,0]
	ds_read_b64_tr_b8 v[156:157], v2 offset:0
	ds_read_b64_tr_b8 v[158:159], v2 offset:0x400
	ds_read_b64_tr_b8 v[160:161], v2 offset:0x800
	ds_read_b64_tr_b8 v[162:163], v2 offset:0xc00
	ds_read_b64_tr_b8 v[148:149], v140 offset:0
	ds_read_b64_tr_b8 v[150:151], v140 offset:0x400
	ds_read_b64_tr_b8 v[152:153], v140 offset:0x800
	ds_read_b64_tr_b8 v[154:155], v140 offset:0xc00
	ds_read_b64_tr_b8 v[140:141], v212 offset:0
	ds_read_b64_tr_b8 v[142:143], v212 offset:0x400
	ds_read_b64_tr_b8 v[144:145], v212 offset:0x800
	ds_read_b64_tr_b8 v[146:147], v212 offset:0xc00
	ds_read_b64_tr_b8 v[132:133], v213 offset:0
	ds_read_b64_tr_b8 v[134:135], v213 offset:0x400
	ds_read_b64_tr_b8 v[136:137], v213 offset:0x800
	ds_read_b64_tr_b8 v[138:139], v213 offset:0xc00
	s_waitcnt lgkmcnt(0)
	s_nop 15
	s_nop 0
	v_max_f32_e32 v2, v85, v85
	v_max_f32_e32 v212, v84, v84
	v_max_f32_e32 v2, v212, v2
	v_max3_f32 v2, v2, v86, v87
	v_max3_f32 v2, v2, v88, v89
	v_max3_f32 v2, v2, v90, v91
	v_max3_f32 v2, v2, v92, v93
	v_max3_f32 v2, v2, v94, v95
	v_max3_f32 v2, v2, v96, v97
	v_max3_f32 v2, v2, v98, v99
	v_max3_f32 v2, v2, v68, v69
	v_max3_f32 v2, v2, v70, v71
	v_max3_f32 v2, v2, v72, v73
	v_max3_f32 v2, v2, v74, v75
	v_max3_f32 v2, v2, v76, v77
	v_max3_f32 v2, v2, v78, v79
	v_max3_f32 v2, v2, v80, v81
	v_max3_f32 v2, v2, v82, v83
	v_mov_b32_e32 v212, v2
	s_nop 1
	v_permlane32_swap_b32_e32 v2, v212
	v_max_f32_e32 v212, v212, v212
	v_max_f32_e32 v2, v2, v2
	v_max_f32_e32 v2, v2, v212
	v_sub_f32_e32 v212, v2, v223
	s_waitcnt vmcnt(2)
	s_lshl_b32 s47, s45, 13
	v_cmp_ge_f32_e32 vcc, s80, v212
	v_add_u32_e32 v212, s47, v206
	s_add_i32 s42, s20, s47
	s_mov_b64 s[8:9], exec
	s_waitcnt vmcnt(3)
	ds_write_b128 v212, v[172:175]
	v_add_u32_e32 v212, s42, v207
	s_waitcnt vmcnt(2)
	ds_write_b128 v212, v[176:179] offset:24576
	s_and_saveexec_b64 s[18:19], s[6:7]
	v_lshl_add_u32 v212, s45, 12, v225
	ds_write_b128 v212, v[164:167] offset:51200
	s_or_b64 exec, exec, s[18:19]
	v_mfma_scale_f32_32x32x64_f8f6f4 v[52:67], v[124:131], v[156:163], v[52:67], v196, v196 op_sel_hi:[0,0,0]
	v_max_f32_e32 v2, v2, v2
	s_cmp_eq_u64 vcc, s[8:9]
	s_cselect_b64 s[8:9], -1, 0
	v_mfma_scale_f32_32x32x64_f8f6f4 v[36:51], v[124:131], v[148:155], v[36:51], v196, v196 op_sel_hi:[0,0,0]
	v_mfma_scale_f32_32x32x64_f8f6f4 v[20:35], v[124:131], v[140:147], v[20:35], v196, v196 op_sel_hi:[0,0,0]
	v_max_f32_e32 v140, v223, v223
	v_max_f32_e32 v2, v140, v2
	v_sub_f32_e32 v140, v223, v2
	v_mul_f32_e32 v140, 0x3dd53b94, v140
	v_exp_f32_e32 v140, v140
	s_nop 0
	v_cndmask_b32_e64 v228, v140, 1.0, s[8:9]
	v_cmp_gt_f32_e32 vcc, 1.0, v228
	v_mfma_scale_f32_32x32x64_f8f6f4 v[4:19], v[124:131], v[132:139], v[4:19], v196, v196 op_sel_hi:[0,0,0]
	s_cbranch_vccz .LBB0_2500
	s_and_saveexec_b64 s[18:19], s[4:5]
	ds_write_b32 v200, v228 offset:49280
	s_or_b64 exec, exec, s[18:19]
	v_add_u32_e32 v124, v189, v199
	s_waitcnt lgkmcnt(0)
	v_add_u32_e32 v132, 0xc080, v124
	v_add_u32_e32 v134, 0xc088, v124
	v_add_u32_e32 v136, 0xc0a0, v124
	v_add_u32_e32 v138, 0xc0a8, v124
	v_add_u32_e32 v125, 0xc0c0, v124
	v_add_u32_e32 v126, 0xc0c8, v124
	v_add_u32_e32 v128, 0xc0e0, v124
	v_add_u32_e32 v130, 0xc0e8, v124
	ds_read2_b32 v[124:125], v125 offset1:1
	ds_read2_b32 v[126:127], v126 offset1:1
	ds_read2_b32 v[128:129], v128 offset1:1
	ds_read2_b32 v[130:131], v130 offset1:1
	ds_read2_b32 v[132:133], v132 offset1:1
	ds_read2_b32 v[134:135], v134 offset1:1
	ds_read2_b32 v[136:137], v136 offset1:1
	ds_read2_b32 v[138:139], v138 offset1:1
	s_waitcnt lgkmcnt(4)
	v_pk_mul_f32 v[66:67], v[66:67], v[130:131]
	v_pk_mul_f32 v[64:65], v[64:65], v[128:129]
	v_pk_mul_f32 v[62:63], v[62:63], v[126:127]
	v_pk_mul_f32 v[60:61], v[60:61], v[124:125]
	s_waitcnt lgkmcnt(0)
	v_pk_mul_f32 v[58:59], v[58:59], v[138:139]
	v_pk_mul_f32 v[56:57], v[56:57], v[136:137]
	v_pk_mul_f32 v[54:55], v[54:55], v[134:135]
	v_pk_mul_f32 v[52:53], v[52:53], v[132:133]
	v_pk_mul_f32 v[50:51], v[50:51], v[130:131]
	v_pk_mul_f32 v[48:49], v[48:49], v[128:129]
	v_pk_mul_f32 v[46:47], v[46:47], v[126:127]
	v_pk_mul_f32 v[44:45], v[44:45], v[124:125]
	v_pk_mul_f32 v[42:43], v[42:43], v[138:139]
	v_pk_mul_f32 v[40:41], v[40:41], v[136:137]
	v_pk_mul_f32 v[38:39], v[38:39], v[134:135]
	v_pk_mul_f32 v[36:37], v[36:37], v[132:133]
	v_pk_mul_f32 v[34:35], v[34:35], v[130:131]
	v_pk_mul_f32 v[32:33], v[32:33], v[128:129]
	v_pk_mul_f32 v[30:31], v[30:31], v[126:127]
	v_pk_mul_f32 v[28:29], v[28:29], v[124:125]
	v_pk_mul_f32 v[26:27], v[26:27], v[138:139]
	v_pk_mul_f32 v[24:25], v[24:25], v[136:137]
	v_pk_mul_f32 v[22:23], v[22:23], v[134:135]
	v_pk_mul_f32 v[20:21], v[20:21], v[132:133]
	v_pk_mul_f32 v[18:19], v[18:19], v[130:131]
	v_pk_mul_f32 v[16:17], v[16:17], v[128:129]
	v_pk_mul_f32 v[14:15], v[14:15], v[126:127]
	v_pk_mul_f32 v[12:13], v[12:13], v[124:125]
	v_pk_mul_f32 v[10:11], v[10:11], v[138:139]
	v_pk_mul_f32 v[8:9], v[8:9], v[136:137]
	v_pk_mul_f32 v[6:7], v[6:7], v[134:135]
	v_pk_mul_f32 v[4:5], v[4:5], v[132:133]

.LBB0_2504:
	s_waitcnt lgkmcnt(9)
	v_mfma_scale_f32_32x32x64_f8f6f4 v[84:99], v[68:75], v[116:123], 0, v196, v196 op_sel_hi:[0,0,0]
	s_add_i32 s8, s45, 1
	s_cmp_lg_u32 s45, 2
	s_cselect_b32 s46, s8, 0
	s_addk_i32 s47, 0xe000
	s_cmp_lg_u32 s45, 0
	s_cselect_b32 s8, s47, 0x4000
	v_add_u32_e32 v194, s8, v203
	v_add_u32_e32 v195, s8, v204
	s_waitcnt lgkmcnt(8)
	v_mfma_scale_f32_32x32x64_f8f6f4 v[68:83], v[76:83], v[116:123], 0, v196, v196 op_sel_hi:[0,0,0]
	s_waitcnt lgkmcnt(5)
	v_mfma_scale_f32_32x32x64_f8f6f4 v[84:99], v[156:163], v[108:115], v[84:99], v196, v196 op_sel_hi:[0,0,0]
	s_waitcnt lgkmcnt(4)
	v_mfma_scale_f32_32x32x64_f8f6f4 v[68:83], v[148:155], v[108:115], v[68:83], v196, v196 op_sel_hi:[0,0,0]
	s_waitcnt lgkmcnt(1)
	v_mfma_scale_f32_32x32x64_f8f6f4 v[84:99], v[140:147], v[100:107], v[84:99], v196, v196 op_sel_hi:[0,0,0]
	v_add_u32_e32 v140, s8, v201
	v_add_u32_e32 v141, s8, v202
	s_waitcnt lgkmcnt(0)
	v_mfma_scale_f32_32x32x64_f8f6f4 v[68:83], v[132:139], v[100:107], v[68:83], v196, v196 op_sel_hi:[0,0,0]
	ds_read_b64_tr_b8 v[156:157], v140 offset:0
	ds_read_b64_tr_b8 v[158:159], v140 offset:0x400
	ds_read_b64_tr_b8 v[160:161], v140 offset:0x800
	ds_read_b64_tr_b8 v[162:163], v140 offset:0xc00
	ds_read_b64_tr_b8 v[148:149], v141 offset:0
	ds_read_b64_tr_b8 v[150:151], v141 offset:0x400
	ds_read_b64_tr_b8 v[152:153], v141 offset:0x800
	ds_read_b64_tr_b8 v[154:155], v141 offset:0xc00
	ds_read_b64_tr_b8 v[140:141], v194 offset:0
	ds_read_b64_tr_b8 v[142:143], v194 offset:0x400
	ds_read_b64_tr_b8 v[144:145], v194 offset:0x800
	ds_read_b64_tr_b8 v[146:147], v194 offset:0xc00
	ds_read_b64_tr_b8 v[132:133], v195 offset:0
	ds_read_b64_tr_b8 v[134:135], v195 offset:0x400
	ds_read_b64_tr_b8 v[136:137], v195 offset:0x800
	ds_read_b64_tr_b8 v[138:139], v195 offset:0xc00
	s_waitcnt lgkmcnt(0)
	s_nop 15
	v_max_f32_e32 v194, v85, v85
	v_max_f32_e32 v195, v84, v84
	v_max_f32_e32 v194, v195, v194
	v_max3_f32 v194, v194, v86, v87
	v_max3_f32 v194, v194, v88, v89
	v_max3_f32 v194, v194, v90, v91
	v_max3_f32 v194, v194, v92, v93
	v_max3_f32 v194, v194, v94, v95
	v_max3_f32 v194, v194, v96, v97
	v_max3_f32 v194, v194, v98, v99
	v_max3_f32 v194, v194, v68, v69
	v_max3_f32 v194, v194, v70, v71
	v_max3_f32 v194, v194, v72, v73
	v_max3_f32 v194, v194, v74, v75
	v_max3_f32 v194, v194, v76, v77
	v_max3_f32 v194, v194, v78, v79
	v_max3_f32 v194, v194, v80, v81
	v_max3_f32 v194, v194, v82, v83
	v_mov_b32_e32 v195, v194
	s_nop 1
	v_permlane32_swap_b32_e32 v194, v195
	v_max_f32_e32 v195, v195, v195
	v_max_f32_e32 v194, v194, v194
	v_max_f32_e32 v194, v194, v195
	v_sub_f32_e32 v195, v194, v2
	v_cmp_ge_f32_e32 vcc, s80, v195
	s_cmp_eq_u64 vcc, exec
	s_cselect_b64 s[8:9], -1, 0
	s_waitcnt vmcnt(2)
	s_lshl_b32 s45, s46, 13
	v_add_u32_e32 v195, s45, v206
	s_waitcnt vmcnt(1)
	ds_write_b128 v195, v[180:183]
	v_add_u32_e32 v180, s45, v208
	s_waitcnt vmcnt(0)
	ds_write_b128 v180, v[184:187] offset:24576
	s_and_saveexec_b64 s[18:19], s[6:7]
	v_lshl_add_u32 v180, s46, 12, v225
	ds_write_b128 v180, v[168:171] offset:51200
	s_or_b64 exec, exec, s[18:19]
	v_mfma_scale_f32_32x32x64_f8f6f4 v[52:67], v[124:131], v[156:163], v[52:67], v196, v196 op_sel_hi:[0,0,0]
	v_mfma_scale_f32_32x32x64_f8f6f4 v[36:51], v[124:131], v[148:155], v[36:51], v196, v196 op_sel_hi:[0,0,0]
	v_mfma_scale_f32_32x32x64_f8f6f4 v[20:35], v[124:131], v[140:147], v[20:35], v196, v196 op_sel_hi:[0,0,0]
	v_max_f32_e32 v140, v2, v2
	v_max_f32_e32 v141, v140, v194
	v_sub_f32_e32 v140, v2, v141
	v_mul_f32_e32 v140, 0x3dd53b94, v140
	v_exp_f32_e32 v140, v140
	s_nop 0
	v_cndmask_b32_e64 v140, v140, 1.0, s[8:9]
	v_cmp_gt_f32_e32 vcc, 1.0, v140
	v_mfma_scale_f32_32x32x64_f8f6f4 v[4:19], v[124:131], v[132:139], v[4:19], v196, v196 op_sel_hi:[0,0,0]
	s_cbranch_vccz .LBB0_2510
	s_and_saveexec_b64 s[18:19], s[4:5]
	ds_write_b32 v200, v140 offset:49280
	s_or_b64 exec, exec, s[18:19]
	v_add_u32_e32 v124, v189, v199
	s_waitcnt lgkmcnt(0)
	v_add_u32_e32 v132, 0xc080, v124
	v_add_u32_e32 v134, 0xc088, v124
	v_add_u32_e32 v136, 0xc0a0, v124
	v_add_u32_e32 v138, 0xc0a8, v124
	v_add_u32_e32 v125, 0xc0c0, v124
	v_add_u32_e32 v126, 0xc0c8, v124
	v_add_u32_e32 v128, 0xc0e0, v124
	v_add_u32_e32 v130, 0xc0e8, v124
	ds_read2_b32 v[124:125], v125 offset1:1
	ds_read2_b32 v[126:127], v126 offset1:1
	ds_read2_b32 v[128:129], v128 offset1:1
	ds_read2_b32 v[130:131], v130 offset1:1
	ds_read2_b32 v[132:133], v132 offset1:1
	ds_read2_b32 v[134:135], v134 offset1:1
	ds_read2_b32 v[136:137], v136 offset1:1
	ds_read2_b32 v[138:139], v138 offset1:1
	s_waitcnt lgkmcnt(4)
	v_pk_mul_f32 v[66:67], v[66:67], v[130:131]
	v_pk_mul_f32 v[64:65], v[64:65], v[128:129]
	v_pk_mul_f32 v[62:63], v[62:63], v[126:127]
	v_pk_mul_f32 v[60:61], v[60:61], v[124:125]
	s_waitcnt lgkmcnt(0)
	v_pk_mul_f32 v[58:59], v[58:59], v[138:139]
	v_pk_mul_f32 v[56:57], v[56:57], v[136:137]
	v_pk_mul_f32 v[54:55], v[54:55], v[134:135]
	v_pk_mul_f32 v[52:53], v[52:53], v[132:133]
	v_pk_mul_f32 v[50:51], v[50:51], v[130:131]
	v_pk_mul_f32 v[48:49], v[48:49], v[128:129]
	v_pk_mul_f32 v[46:47], v[46:47], v[126:127]
	v_pk_mul_f32 v[44:45], v[44:45], v[124:125]
	v_pk_mul_f32 v[42:43], v[42:43], v[138:139]
	v_pk_mul_f32 v[40:41], v[40:41], v[136:137]
	v_pk_mul_f32 v[38:39], v[38:39], v[134:135]
	v_pk_mul_f32 v[36:37], v[36:37], v[132:133]
	v_pk_mul_f32 v[34:35], v[34:35], v[130:131]
	v_pk_mul_f32 v[32:33], v[32:33], v[128:129]
	v_pk_mul_f32 v[30:31], v[30:31], v[126:127]
	v_pk_mul_f32 v[28:29], v[28:29], v[124:125]
	v_pk_mul_f32 v[26:27], v[26:27], v[138:139]
	v_pk_mul_f32 v[24:25], v[24:25], v[136:137]
	v_pk_mul_f32 v[22:23], v[22:23], v[134:135]
	v_pk_mul_f32 v[20:21], v[20:21], v[132:133]
	v_pk_mul_f32 v[18:19], v[18:19], v[130:131]
	v_pk_mul_f32 v[16:17], v[16:17], v[128:129]
	v_pk_mul_f32 v[14:15], v[14:15], v[126:127]
	v_pk_mul_f32 v[12:13], v[12:13], v[124:125]
	v_pk_mul_f32 v[10:11], v[10:11], v[138:139]
	v_pk_mul_f32 v[8:9], v[8:9], v[136:137]
	v_pk_mul_f32 v[6:7], v[6:7], v[134:135]
	v_pk_mul_f32 v[4:5], v[4:5], v[132:133]

.LBB0_2513:
	s_ashr_i32 s4, s69, 6
	s_ashr_i32 s5, s4, 31
	s_lshl_b32 s6, s69, 8
	s_lshl_b64 s[4:5], s[4:5], 11
	s_and_b32 s6, s6, 0x300
	s_lshl_b32 s100, s69, 5
	s_and_b32 s100, s100, 0x400
	s_or_b32 s6, s6, s100
	s_or_b32 s4, s4, s6
	s_add_u32 s40, s4, 0x2000
	s_addc_u32 s41, s5, 0
	s_mov_b32 s71, 1
	s_andn2_b64 vcc, exec, s[24:25]
	s_mov_b64 s[4:5], s[40:41]
	s_cbranch_vccz .LBB0_2476
	s_branch .LBB0_2477

.LBB0_2655:
	s_andn2_b64 vcc, exec, s[4:5]
	s_cbranch_vccnz .LBB0_2657
	s_ashr_i32 s4, s68, 6
	s_ashr_i32 s5, s4, 31
	s_lshl_b32 s6, s68, 8
	s_lshl_b64 s[4:5], s[4:5], 11
	s_and_b32 s6, s6, 0x300
	s_lshl_b32 s100, s68, 5
	s_and_b32 s100, s100, 0x400
	s_or_b32 s6, s6, s100
	s_or_b32 s4, s4, s6
	s_add_u32 s24, s4, 0x2000
	s_addc_u32 s25, s5, 0

.LBB0_2659:
	s_lshr_b32 s18, s68, 2
	s_and_b64 s[6:7], s[8:9], exec
	s_cselect_b32 s18, s18, s68
	s_and_b32 s19, s18, 7
	s_lshl_b64 s[6:7], s[24:25], 10
	s_add_u32 s6, s52, s6
	s_addc_u32 s7, s53, s7
	s_lshl_b32 s69, s19, 7
	s_add_u32 s38, s6, s69
	s_addc_u32 s39, s7, 0
	s_lshl_b64 s[6:7], s[4:5], 8
	s_add_u32 s4, s56, s6
	s_addc_u32 s5, s57, s7
	s_lshl_b32 s18, s18, 5
	s_and_b32 s18, s18, 0x80
	s_add_u32 s4, s4, s18
	s_addc_u32 s5, s5, 0
	v_mov_b32_e32 v163, v0
	s_add_u32 s19, s58, s6
	s_addc_u32 s35, s59, s7
	v_ashrrev_i32_e32 v14, 3, v163
	v_and_b32_e32 v2, 7, v163
	v_ashrrev_i32_e32 v15, 31, v14
	s_add_u32 s34, s19, s18
	v_lshlrev_b32_e32 v2, 4, v2
	v_lshlrev_b64 v[52:53], 8, v[14:15]
	s_addc_u32 s35, s35, 0
	v_or_b32_e32 v54, v52, v2
	v_mov_b32_e32 v55, v53
	v_mov_b32_e32 v162, 0x7f7f7f7f
	v_lshl_add_u64 v[4:5], s[34:35], 0, v[54:55]
	v_lshl_add_u64 v[10:11], s[4:5], 0, v[54:55]
	global_load_dwordx4 v[6:9], v[4:5], off
	s_nop 0
	global_load_dwordx4 v[10:13], v[10:11], off
	v_ashrrev_i32_e32 v15, 1, v163
	v_bfi_b32 v4, s31, v15, v163
	v_ashrrev_i32_e32 v5, 31, v4
	v_lshlrev_b64 v[4:5], 10, v[4:5]
	v_lshl_add_u64 v[16:17], s[38:39], 0, v[4:5]
	v_and_b32_e32 v4, 32, v163
	v_mov_b32_e32 v5, v3
	v_lshl_add_u64 v[16:17], v[16:17], 0, v[4:5]
	global_load_dwordx4 v[112:115], v[16:17], off offset:16
	global_load_dwordx4 v[108:111], v[16:17], off
	global_load_dwordx4 v[104:107], v[16:17], off offset:80
	global_load_dwordx4 v[100:103], v[16:17], off offset:64
	v_bfe_u32 v5, v163, 1, 2
	v_lshrrev_b32_e32 v17, 4, v163
	v_and_b32_e32 v74, 31, v163
	v_lshlrev_b32_e32 v18, 4, v163
	v_bitop3_b32 v5, v5, v17, 3 bitop3:0x78
	v_lshlrev_b32_e32 v16, 3, v163
	v_lshlrev_b32_e32 v14, 7, v14
	v_and_b32_e32 v17, 16, v18
	v_lshlrev_b32_e32 v172, 7, v74
	v_lshlrev_b32_e32 v5, 5, v5
	v_and_b32_e32 v19, 0x70, v163
	v_bitop3_b32 v173, v16, v4, s87 bitop3:0x6c
	v_or_b32_e32 v18, 16, v4
	v_add_u32_e32 v176, s20, v172
	v_or3_b32 v5, v5, v17, v14
	v_bitop3_b32 v175, v2, v14, v19 bitop3:0xde
	v_bitop3_b32 v174, v16, v18, s87 bitop3:0x6c
	v_add_u32_e32 v14, v176, v173
	v_add_u32_e32 v178, s20, v5
	v_add_u32_e32 v177, s20, v175
	v_add_u32_e32 v17, v176, v174
	s_waitcnt vmcnt(0)
	v_and_b32_e32 v5, 0x3fffffc0, v163
	s_mov_b64 s[46:47], 0x4000
	v_lshl_add_u32 v157, v5, 2, s20
	v_and_b32_e32 v156, 0xffffffe0, v15
	s_mov_b32 s37, s36
	s_mov_b32 s38, s36
	s_mov_b32 s39, s36
	s_mov_b32 s40, s36
	s_mov_b32 s41, s36
	s_mov_b32 s42, s36
	s_mov_b32 s43, s36
	s_mov_b32 s44, s36
	s_mov_b32 s45, s36
	s_mov_b32 s48, s36
	s_mov_b32 s49, s36
	s_mov_b32 s50, s36
	s_mov_b32 s51, s36
	v_and_b32_e32 v75, 63, v163
	v_bfe_u32 v164, v163, 5, 1
	v_lshl_add_u32 v170, v74, 2, v157
	v_lshlrev_b32_e32 v169, 4, v164
	v_mov_b32_e32 v171, 0
	s_waitcnt vmcnt(0)
	ds_write_b128 v178, v[6:9]
	ds_write_b128 v177, v[10:13] offset:24576
	s_waitcnt lgkmcnt(0)
	s_barrier
	ds_read_b128 v[6:9], v14 offset:24576
	ds_read_b128 v[10:13], v17 offset:24576
	s_waitcnt lgkmcnt(0)
	v_mfma_scale_f32_32x32x64_f8f6f4 v[20:35], v[6:13], v[108:115], 0, v162, v162 op_sel_hi:[0,0,0]
	v_lshrrev_b32_e32 v6, 1, v163
	v_and_or_b32 v5, v6, 7, v4
	v_lshl_add_u64 v[6:7], v[54:55], 0, s[46:47]
	v_lshl_add_u64 v[8:9], s[4:5], 0, v[6:7]
	v_lshl_add_u64 v[6:7], s[34:35], 0, v[6:7]
	ds_read_b128 v[36:39], v14 offset:28672
	ds_read_b128 v[40:43], v17 offset:28672
	global_load_dwordx4 v[64:67], v[6:7], off
	global_load_dwordx4 v[68:71], v[8:9], off
	v_or_b32_e32 v6, 64, v4
	v_or_b32_e32 v4, 0x50, v4
	v_bitop3_b32 v180, v16, v6, s87 bitop3:0x6c
	v_lshl_add_u64 v[54:55], v[54:55], 0, s[60:61]
	v_bitop3_b32 v179, v16, v4, s87 bitop3:0x6c
	v_add_u32_e32 v18, v176, v180
	v_lshl_add_u64 v[72:73], s[4:5], 0, v[54:55]
	v_lshlrev_b32_e32 v15, 7, v5
	v_add_u32_e32 v19, v176, v179
	ds_read_b128 v[4:7], v18 offset:24576
	ds_read_b128 v[8:11], v19 offset:24576
	ds_read_b128 v[56:59], v18 offset:28672
	ds_read_b128 v[60:63], v19 offset:28672
	v_lshl_add_u64 v[54:55], s[34:35], 0, v[54:55]
	global_load_dwordx4 v[144:147], v[72:73], off
	global_load_dwordx4 v[140:143], v[54:55], off
	s_waitcnt lgkmcnt(4)
	v_mfma_scale_f32_32x32x64_f8f6f4 v[36:51], v[36:43], v[108:115], 0, v162, v162 op_sel_hi:[0,0,0]
	v_and_b32_e32 v12, 16, v163
	v_and_b32_e32 v14, 8, v16
	v_and_b32_e32 v13, 0x60, v16
	v_add3_u32 v17, v12, s20, v14
	v_or3_b32 v12, v14, v12, v15
	v_add3_u32 v165, v17, v15, v13
	v_or_b32_e32 v13, v12, v13
	v_bitop3_b32 v12, v12, s30, v16 bitop3:0x34
	v_xad_u32 v166, v13, 32, s20
	v_xad_u32 v167, v13, 64, s20
	v_add_u32_e32 v168, s20, v12
	s_mov_b32 s46, s36
	s_mov_b32 s47, s36
	s_waitcnt vmcnt(2)
	v_cmp_gt_u32_e64 s[4:5], 32, v75
	s_waitcnt lgkmcnt(2)
	v_mfma_scale_f32_32x32x64_f8f6f4 v[20:35], v[4:11], v[100:107], v[20:35], v162, v162 op_sel_hi:[0,0,0]
	v_mov_b64_e32 v[4:5], s[36:37]
	v_mov_b64_e32 v[18:19], s[50:51]
	v_mov_b64_e32 v[6:7], s[38:39]
	v_mov_b64_e32 v[8:9], s[40:41]
	v_mov_b64_e32 v[10:11], s[42:43]
	v_mov_b64_e32 v[12:13], s[44:45]
	v_mov_b64_e32 v[14:15], s[46:47]
	v_mov_b64_e32 v[16:17], s[48:49]
	s_mov_b32 s37, 1
	s_waitcnt vmcnt(3)
	ds_write_b128 v178, v[64:67] offset:8192
	s_waitcnt vmcnt(2)
	ds_write_b128 v177, v[68:71] offset:32768
	s_waitcnt lgkmcnt(2)
	v_mfma_scale_f32_32x32x64_f8f6f4 v[36:51], v[56:63], v[100:107], v[36:51], v162, v162 op_sel_hi:[0,0,0]
	s_nop 4
	v_max_f32_e32 v54, v21, v21
	v_max_f32_e32 v55, v20, v20
	v_max_f32_e32 v54, v55, v54
	v_max3_f32 v54, v54, v22, v23
	v_max3_f32 v54, v54, v24, v25
	v_max3_f32 v54, v54, v26, v27
	v_max3_f32 v54, v54, v28, v29
	v_max3_f32 v54, v54, v30, v31
	v_max3_f32 v54, v54, v32, v33
	v_max3_f32 v54, v54, v34, v35
	s_waitcnt lgkmcnt(0)
	s_barrier
	s_nop 2
	v_max3_f32 v54, v54, v36, v37
	v_max3_f32 v54, v54, v38, v39
	v_max3_f32 v54, v54, v40, v41
	v_max3_f32 v54, v54, v42, v43
	v_max3_f32 v54, v54, v44, v45
	v_max3_f32 v54, v54, v46, v47
	v_max3_f32 v54, v54, v48, v49
	v_max3_f32 v54, v54, v50, v51
	v_mov_b32_e32 v55, v54
	s_nop 1
	v_permlane32_swap_b32_e32 v54, v55
	v_max_f32_e32 v55, v55, v55
	v_max_f32_e32 v54, v54, v54
	v_max_f32_e32 v54, v54, v55
	v_add_f32_e32 v55, 0x7149f2ca, v54
	v_cmp_ge_f32_e32 vcc, s81, v55
	s_cmp_eq_u64 vcc, exec
	v_max_f32_e32 v56, 0xf149f2ca, v54
	s_cselect_b64 vcc, -1, 0
	v_cndmask_b32_e32 v132, v56, v248, vcc
	v_mul_f32_e32 v54, 0xbe0293ee, v132
	v_fmamk_f32 v20, v20, 0x3e0293ee, v54
	v_exp_f32_e32 v154, v20
	v_fmamk_f32 v20, v22, 0x3e0293ee, v54
	v_exp_f32_e32 v160, v20
	v_fmamk_f32 v20, v23, 0x3e0293ee, v54
	v_exp_f32_e32 v161, v20
	v_fmamk_f32 v20, v24, 0x3e0293ee, v54
	v_exp_f32_e32 v150, v20
	v_fmamk_f32 v20, v25, 0x3e0293ee, v54
	v_exp_f32_e32 v151, v20
	v_fmamk_f32 v20, v26, 0x3e0293ee, v54
	v_exp_f32_e32 v152, v20
	v_fmamk_f32 v20, v27, 0x3e0293ee, v54
	v_exp_f32_e32 v153, v20
	v_fmamk_f32 v20, v28, 0x3e0293ee, v54
	v_exp_f32_e32 v138, v20
	v_fmamk_f32 v20, v29, 0x3e0293ee, v54
	v_exp_f32_e32 v139, v20
	v_fmamk_f32 v20, v30, 0x3e0293ee, v54
	v_exp_f32_e32 v148, v20
	v_fmamk_f32 v20, v31, 0x3e0293ee, v54
	v_exp_f32_e32 v149, v20
	v_fmamk_f32 v20, v32, 0x3e0293ee, v54
	v_exp_f32_e32 v134, v20
	v_fmamk_f32 v20, v33, 0x3e0293ee, v54
	v_exp_f32_e32 v135, v20
	v_fmamk_f32 v20, v34, 0x3e0293ee, v54
	v_exp_f32_e32 v136, v20
	v_fmamk_f32 v20, v35, 0x3e0293ee, v54
	v_exp_f32_e32 v137, v20
	v_sub_f32_e32 v20, 0xf149f2ca, v56
	v_mul_f32_e32 v20, 0x3e0293ee, v20
	v_exp_f32_e32 v20, v20
	s_add_u32 s18, s66, s18
	v_fmamk_f32 v21, v21, 0x3e0293ee, v54
	s_addc_u32 s19, s67, 0
	v_exp_f32_e32 v155, v21
	s_add_u32 s6, s18, s6
	s_addc_u32 s7, s19, s7
	v_pk_fma_f32 v[116:117], v[50:51], s[72:73], v[54:55] op_sel_hi:[1,0,0]
	v_pk_fma_f32 v[118:119], v[48:49], s[72:73], v[54:55] op_sel_hi:[1,0,0]
	v_pk_fma_f32 v[120:121], v[46:47], s[72:73], v[54:55] op_sel_hi:[1,0,0]
	v_pk_fma_f32 v[122:123], v[44:45], s[72:73], v[54:55] op_sel_hi:[1,0,0]
	v_pk_fma_f32 v[124:125], v[42:43], s[72:73], v[54:55] op_sel_hi:[1,0,0]
	v_pk_fma_f32 v[126:127], v[40:41], s[72:73], v[54:55] op_sel_hi:[1,0,0]
	v_pk_fma_f32 v[128:129], v[38:39], s[72:73], v[54:55] op_sel_hi:[1,0,0]
	v_pk_fma_f32 v[130:131], v[36:37], s[72:73], v[54:55] op_sel_hi:[1,0,0]
	v_cndmask_b32_e64 v181, v20, 1.0, vcc
	v_lshl_add_u64 v[158:159], s[6:7], 0, v[52:53]
	v_mov_b64_e32 v[66:67], v[18:19]
	v_mov_b64_e32 v[50:51], v[18:19]
	v_mov_b64_e32 v[34:35], v[18:19]
	v_mov_b64_e32 v[64:65], v[16:17]
	v_mov_b64_e32 v[62:63], v[14:15]
	v_mov_b64_e32 v[60:61], v[12:13]
	v_mov_b64_e32 v[58:59], v[10:11]
	v_mov_b64_e32 v[56:57], v[8:9]
	v_mov_b64_e32 v[54:55], v[6:7]
	v_mov_b64_e32 v[52:53], v[4:5]
	v_mov_b64_e32 v[48:49], v[16:17]
	v_mov_b64_e32 v[46:47], v[14:15]
	v_mov_b64_e32 v[44:45], v[12:13]
	v_mov_b64_e32 v[42:43], v[10:11]
	v_mov_b64_e32 v[40:41], v[8:9]
	v_mov_b64_e32 v[38:39], v[6:7]
	v_mov_b64_e32 v[36:37], v[4:5]
	v_mov_b64_e32 v[32:33], v[16:17]
	v_mov_b64_e32 v[30:31], v[14:15]
	v_mov_b64_e32 v[28:29], v[12:13]
	v_mov_b64_e32 v[26:27], v[10:11]
	v_mov_b64_e32 v[24:25], v[8:9]
	v_mov_b64_e32 v[22:23], v[6:7]
	v_mov_b64_e32 v[20:21], v[4:5]
.LBB0_2660:
	s_add_i32 s6, s71, 1
	s_cmp_lg_u32 s71, 2
	s_cselect_b32 s38, s6, 0
	s_lshl_b32 s6, s71, 13
	s_add_i32 s7, s6, 0xffffe000
	s_cmp_lg_u32 s71, 0
	s_cselect_b32 s7, s7, 0x4000
	v_add_u32_e32 v133, s7, v165
	v_add_u32_e32 v198, s7, v166
	v_add_u32_e32 v199, s7, v167
	v_add_u32_e32 v200, s7, v168
	v_add_u32_e32 v186, s6, v176
	v_add_u32_e32 v76, v186, v173
	ds_read_b128 v[68:71], v76 offset:24576
	v_add_u32_e32 v80, v186, v174
	ds_read_b128 v[72:75], v80 offset:24576
	ds_read_b128 v[76:79], v76 offset:28672
	ds_read_b128 v[80:83], v80 offset:28672
	v_add_u32_e32 v190, v186, v180
	ds_read_b128 v[182:185], v190 offset:24576
	v_add_u32_e32 v194, v186, v179
	ds_read_b128 v[186:189], v194 offset:24576
	ds_read_b128 v[190:193], v190 offset:28672
	ds_read_b128 v[194:197], v194 offset:28672
	v_exp_f32_e32 v130, v130
	v_exp_f32_e32 v131, v131
	s_waitcnt lgkmcnt(6)
	v_mfma_scale_f32_32x32x64_f8f6f4 v[84:99], v[68:75], v[108:115], 0, v162, v162 op_sel_hi:[0,0,0]
	v_exp_f32_e32 v128, v128
	v_exp_f32_e32 v129, v129
	v_exp_f32_e32 v126, v126
	v_exp_f32_e32 v127, v127
	v_exp_f32_e32 v124, v124
	v_exp_f32_e32 v125, v125
	v_exp_f32_e32 v122, v122
	v_exp_f32_e32 v123, v123
	s_waitcnt lgkmcnt(2)
	v_mfma_scale_f32_32x32x64_f8f6f4 v[84:99], v[182:189], v[100:107], v[84:99], v162, v162 op_sel_hi:[0,0,0]
	v_exp_f32_e32 v188, v116
	v_add_f32_e32 v116, 0, v154
	v_add_f32_e32 v116, v155, v116
	v_add_f32_e32 v116, v160, v116
	v_add_f32_e32 v116, v161, v116
	v_add_f32_e32 v116, v150, v116
	v_add_f32_e32 v116, v151, v116
	v_add_f32_e32 v116, v152, v116
	v_add_f32_e32 v116, v153, v116
	v_add_f32_e32 v116, v138, v116
	v_add_f32_e32 v116, v139, v116
	v_add_f32_e32 v116, v148, v116
	v_add_f32_e32 v116, v149, v116
	v_add_f32_e32 v116, v134, v116
	v_add_f32_e32 v116, v135, v116
	v_mfma_scale_f32_32x32x64_f8f6f4 v[68:83], v[76:83], v[108:115], 0, v162, v162 op_sel_hi:[0,0,0]
	v_add_f32_e32 v116, v136, v116
	v_add_f32_e32 v116, v137, v116
	v_add_f32_e32 v116, v130, v116
	v_add_f32_e32 v116, v131, v116
	v_add_f32_e32 v116, v128, v116
	v_add_f32_e32 v116, v129, v116
	v_add_f32_e32 v116, v126, v116
	v_add_f32_e32 v116, v127, v116
	v_exp_f32_e32 v184, v120
	v_add_f32_e32 v116, v124, v116
	v_exp_f32_e32 v185, v121
	v_add_f32_e32 v116, v125, v116
	v_exp_f32_e32 v186, v118
	v_add_f32_e32 v116, v122, v116
	v_exp_f32_e32 v187, v119
	s_waitcnt lgkmcnt(0)
	v_mfma_scale_f32_32x32x64_f8f6f4 v[68:83], v[190:197], v[100:107], v[68:83], v162, v162 op_sel_hi:[0,0,0]
	v_add_f32_e32 v116, v123, v116
	v_add_f32_e32 v116, v184, v116
	v_exp_f32_e32 v189, v117
	v_add_f32_e32 v116, v185, v116
	v_add_f32_e32 v116, v186, v116
	v_add_f32_e32 v116, v187, v116
	v_add_f32_e32 v116, v188, v116
	v_add_f32_e32 v182, v189, v116
	v_mov_b32_e32 v116, 0
	v_mov_b32_e32 v117, 0
	v_mov_b32_e32 v121, 0
	v_cvt_pk_fp8_f32 v116, v154, v155
	v_cvt_pk_fp8_f32 v117, v130, v131
	v_mov_b32_e32 v118, 0
	v_mov_b32_e32 v119, 0
	v_mov_b32_e32 v120, 0
	v_cvt_pk_fp8_f32 v121, v122, v123
	v_mov_b32_e32 v122, 0
	v_mov_b32_e32 v123, 0
	v_cvt_pk_fp8_f32 v118, v150, v151
	v_cvt_pk_fp8_f32 v119, v126, v127
	v_cvt_pk_fp8_f32 v120, v138, v139
	v_cvt_pk_fp8_f32 v122, v134, v135
	v_cvt_pk_fp8_f32 v123, v186, v187
	v_cvt_pk_fp8_f32 v116, v160, v161 op_sel:[0,0,1]
	v_cvt_pk_fp8_f32 v117, v128, v129 op_sel:[0,0,1]
	v_cvt_pk_fp8_f32 v118, v152, v153 op_sel:[0,0,1]
	v_cvt_pk_fp8_f32 v119, v124, v125 op_sel:[0,0,1]
	v_cvt_pk_fp8_f32 v120, v148, v149 op_sel:[0,0,1]
	v_cvt_pk_fp8_f32 v121, v184, v185 op_sel:[0,0,1]
	v_cvt_pk_fp8_f32 v122, v136, v137 op_sel:[0,0,1]
	v_cvt_pk_fp8_f32 v123, v188, v189 op_sel:[0,0,1]
	v_mov_b32_e32 v183, v182
	s_nop 1
	v_permlane32_swap_b32_e32 v182, v183
	v_permlane32_swap_b32_e32 v116, v117
	v_permlane32_swap_b32_e32 v118, v119
	v_permlane32_swap_b32_e32 v120, v121
	v_permlane32_swap_b32_e32 v122, v123
	v_lshl_add_u64 v[160:161], v[158:159], 0, v[2:3]
	s_mov_b32 s6, 0x3a80c000
	v_add_co_u32_e32 v124, vcc, s6, v160
	s_mov_b32 s6, 0x3840c000
	s_nop 0
	v_addc_co_u32_e32 v125, vcc, 0, v161, vcc
	v_add_co_u32_e32 v126, vcc, s6, v160
	s_nop 1
	v_addc_co_u32_e32 v127, vcc, 0, v161, vcc
	global_load_dwordx4 v[148:151], v[124:125], off
	global_load_dwordx4 v[152:155], v[126:127], off
	ds_read_b64_tr_b8 v[124:125], v133 offset:0
	ds_read_b64_tr_b8 v[126:127], v133 offset:0x400
	ds_read_b64_tr_b8 v[128:129], v133 offset:0x800
	ds_read_b64_tr_b8 v[130:131], v133 offset:0xc00
	ds_read_b64_tr_b8 v[202:203], v198 offset:0
	ds_read_b64_tr_b8 v[204:205], v198 offset:0x400
	ds_read_b64_tr_b8 v[206:207], v198 offset:0x800
	ds_read_b64_tr_b8 v[208:209], v198 offset:0xc00
	ds_read_b64_tr_b8 v[210:211], v199 offset:0
	ds_read_b64_tr_b8 v[212:213], v199 offset:0x400
	ds_read_b64_tr_b8 v[214:215], v199 offset:0x800
	ds_read_b64_tr_b8 v[216:217], v199 offset:0xc00
	ds_read_b64_tr_b8 v[218:219], v200 offset:0
	ds_read_b64_tr_b8 v[220:221], v200 offset:0x400
	ds_read_b64_tr_b8 v[222:223], v200 offset:0x800
	ds_read_b64_tr_b8 v[224:225], v200 offset:0xc00
	s_waitcnt lgkmcnt(12)
	s_nop 0
	v_mfma_scale_f32_32x32x64_f8f6f4 v[4:19], v[116:123], v[124:131], v[4:19], v162, v162 op_sel_hi:[0,0,0]
	s_waitcnt lgkmcnt(8)
	s_nop 0
	v_mfma_scale_f32_32x32x64_f8f6f4 v[52:67], v[116:123], v[202:209], v[52:67], v162, v162 op_sel_hi:[0,0,0]
	s_waitcnt lgkmcnt(4)
	s_nop 0
	v_mfma_scale_f32_32x32x64_f8f6f4 v[36:51], v[116:123], v[210:217], v[36:51], v162, v162 op_sel_hi:[0,0,0]
	s_waitcnt lgkmcnt(0)
	s_nop 0
	v_mfma_scale_f32_32x32x64_f8f6f4 v[20:35], v[116:123], v[218:225], v[20:35], v162, v162 op_sel_hi:[0,0,0]
	v_max_f32_e32 v116, v85, v85
	v_max_f32_e32 v117, v84, v84
	v_max_f32_e32 v116, v117, v116
	v_max3_f32 v116, v116, v86, v87
	v_max3_f32 v116, v116, v88, v89
	v_max3_f32 v116, v116, v90, v91
	v_max3_f32 v116, v116, v92, v93
	v_max3_f32 v116, v116, v94, v95
	v_max3_f32 v116, v116, v96, v97
	v_max3_f32 v116, v116, v98, v99
	v_max3_f32 v116, v116, v68, v69
	v_max3_f32 v116, v116, v70, v71
	v_max3_f32 v116, v116, v72, v73
	v_max3_f32 v116, v116, v74, v75
	v_max3_f32 v116, v116, v76, v77
	v_max3_f32 v116, v116, v78, v79
	v_max3_f32 v116, v116, v80, v81
	v_max3_f32 v116, v116, v82, v83
	v_mov_b32_e32 v117, v116
	s_nop 1
	v_permlane32_swap_b32_e32 v116, v117
	v_max_f32_e32 v117, v117, v117
	v_max_f32_e32 v116, v116, v116
	v_max_f32_e32 v116, v116, v117
	v_sub_f32_e32 v117, v116, v132
	v_cmp_ge_f32_e32 vcc, s81, v117
	v_max_f32_e32 v117, v132, v132
	v_max_f32_e32 v116, v117, v116
	v_sub_f32_e32 v117, v132, v116
	v_mul_f32_e32 v117, 0x3e0293ee, v117
	v_exp_f32_e32 v117, v117
	s_cmp_eq_u64 vcc, exec
	s_cselect_b64 s[6:7], -1, 0
	s_waitcnt vmcnt(2)
	s_lshl_b32 s39, s38, 13
	v_cndmask_b32_e64 v184, v117, 1.0, s[6:7]
	v_add_u32_e32 v117, s39, v178
	s_add_i32 s34, s20, s39
	s_waitcnt vmcnt(2)
	ds_write_b128 v117, v[140:143]
	v_add_u32_e32 v117, s34, v175
	v_cmp_gt_f32_e32 vcc, 1.0, v184
	ds_write_b128 v117, v[144:147] offset:24576
	s_cbranch_vccz .LBB0_2664
	s_and_saveexec_b64 s[18:19], s[4:5]
	ds_write_b32 v170, v184 offset:49280
	s_or_b64 exec, exec, s[18:19]
	v_add_u32_e32 v117, v157, v169
	s_waitcnt lgkmcnt(0)
	v_add_u32_e32 v126, 0xc080, v117
	v_add_u32_e32 v128, 0xc088, v117
	v_add_u32_e32 v130, 0xc0a0, v117
	v_add_u32_e32 v118, 0xc0c0, v117
	v_add_u32_e32 v120, 0xc0c8, v117
	v_add_u32_e32 v122, 0xc0e0, v117
	v_add_u32_e32 v133, 0xc0a8, v117
	v_add_u32_e32 v117, 0xc0e8, v117
	ds_read2_b32 v[118:119], v118 offset1:1
	ds_read2_b32 v[120:121], v120 offset1:1
	ds_read2_b32 v[122:123], v122 offset1:1
	ds_read2_b32 v[124:125], v117 offset1:1
	ds_read2_b32 v[126:127], v126 offset1:1
	ds_read2_b32 v[128:129], v128 offset1:1
	ds_read2_b32 v[130:131], v130 offset1:1
	ds_read2_b32 v[134:135], v133 offset1:1
	s_waitcnt lgkmcnt(4)
	v_pk_mul_f32 v[18:19], v[18:19], v[124:125]
	v_pk_mul_f32 v[16:17], v[16:17], v[122:123]
	v_pk_mul_f32 v[14:15], v[14:15], v[120:121]
	v_pk_mul_f32 v[12:13], v[12:13], v[118:119]
	s_waitcnt lgkmcnt(0)
	v_pk_mul_f32 v[10:11], v[10:11], v[134:135]
	v_pk_mul_f32 v[8:9], v[8:9], v[130:131]
	v_pk_mul_f32 v[6:7], v[6:7], v[128:129]
	v_pk_mul_f32 v[4:5], v[4:5], v[126:127]
	v_pk_mul_f32 v[66:67], v[66:67], v[124:125]
	v_pk_mul_f32 v[64:65], v[64:65], v[122:123]
	v_pk_mul_f32 v[62:63], v[62:63], v[120:121]
	v_pk_mul_f32 v[60:61], v[60:61], v[118:119]
	v_pk_mul_f32 v[58:59], v[58:59], v[134:135]
	v_pk_mul_f32 v[56:57], v[56:57], v[130:131]
	v_pk_mul_f32 v[54:55], v[54:55], v[128:129]
	v_pk_mul_f32 v[52:53], v[52:53], v[126:127]
	v_pk_mul_f32 v[50:51], v[50:51], v[124:125]
	v_pk_mul_f32 v[48:49], v[48:49], v[122:123]
	v_pk_mul_f32 v[46:47], v[46:47], v[120:121]
	v_pk_mul_f32 v[44:45], v[44:45], v[118:119]
	v_pk_mul_f32 v[42:43], v[42:43], v[134:135]
	v_pk_mul_f32 v[40:41], v[40:41], v[130:131]
	v_pk_mul_f32 v[38:39], v[38:39], v[128:129]
	v_pk_mul_f32 v[36:37], v[36:37], v[126:127]
	v_pk_mul_f32 v[34:35], v[34:35], v[124:125]
	v_pk_mul_f32 v[32:33], v[32:33], v[122:123]
	v_pk_mul_f32 v[30:31], v[30:31], v[120:121]
	v_pk_mul_f32 v[28:29], v[28:29], v[118:119]
	v_pk_mul_f32 v[26:27], v[26:27], v[134:135]
	v_pk_mul_f32 v[24:25], v[24:25], v[130:131]
	v_pk_mul_f32 v[22:23], v[22:23], v[128:129]
	v_pk_mul_f32 v[20:21], v[20:21], v[126:127]

.LBB0_2666:
	s_waitcnt lgkmcnt(5)
	v_mfma_scale_f32_32x32x64_f8f6f4 v[84:99], v[68:75], v[108:115], 0, v162, v162 op_sel_hi:[0,0,0]
	s_add_i32 s6, s38, 1
	s_cmp_lg_u32 s38, 2
	s_cselect_b32 s71, s6, 0
	s_addk_i32 s39, 0xe000
	s_cmp_lg_u32 s38, 0
	s_cselect_b32 s6, s39, 0x4000
	s_waitcnt lgkmcnt(4)
	v_mfma_scale_f32_32x32x64_f8f6f4 v[68:83], v[76:83], v[108:115], 0, v162, v162 op_sel_hi:[0,0,0]
	s_waitcnt lgkmcnt(1)
	v_mfma_scale_f32_32x32x64_f8f6f4 v[84:99], v[132:139], v[100:107], v[84:99], v162, v162 op_sel_hi:[0,0,0]
	v_add_u32_e32 v133, s6, v166
	v_add_u32_e32 v132, s6, v165
	v_add_u32_e32 v134, s6, v167
	v_add_u32_e32 v135, s6, v168
	s_waitcnt lgkmcnt(0)
	v_mfma_scale_f32_32x32x64_f8f6f4 v[68:83], v[124:131], v[100:107], v[68:83], v162, v162 op_sel_hi:[0,0,0]
	ds_read_b64_tr_b8 v[124:125], v132 offset:0
	ds_read_b64_tr_b8 v[126:127], v132 offset:0x400
	ds_read_b64_tr_b8 v[128:129], v132 offset:0x800
	ds_read_b64_tr_b8 v[130:131], v132 offset:0xc00
	ds_read_b64_tr_b8 v[202:203], v133 offset:0
	ds_read_b64_tr_b8 v[204:205], v133 offset:0x400
	ds_read_b64_tr_b8 v[206:207], v133 offset:0x800
	ds_read_b64_tr_b8 v[208:209], v133 offset:0xc00
	ds_read_b64_tr_b8 v[210:211], v134 offset:0
	ds_read_b64_tr_b8 v[212:213], v134 offset:0x400
	ds_read_b64_tr_b8 v[214:215], v134 offset:0x800
	ds_read_b64_tr_b8 v[216:217], v134 offset:0xc00
	ds_read_b64_tr_b8 v[218:219], v135 offset:0
	ds_read_b64_tr_b8 v[220:221], v135 offset:0x400
	ds_read_b64_tr_b8 v[222:223], v135 offset:0x800
	ds_read_b64_tr_b8 v[224:225], v135 offset:0xc00
	s_waitcnt lgkmcnt(12)
	s_nop 0
	v_mfma_scale_f32_32x32x64_f8f6f4 v[4:19], v[116:123], v[124:131], v[4:19], v162, v162 op_sel_hi:[0,0,0]
	s_waitcnt lgkmcnt(8)
	s_nop 0
	v_mfma_scale_f32_32x32x64_f8f6f4 v[52:67], v[116:123], v[202:209], v[52:67], v162, v162 op_sel_hi:[0,0,0]
	s_waitcnt lgkmcnt(4)
	s_nop 0
	v_mfma_scale_f32_32x32x64_f8f6f4 v[36:51], v[116:123], v[210:217], v[36:51], v162, v162 op_sel_hi:[0,0,0]
	s_waitcnt lgkmcnt(0)
	s_nop 0
	v_mfma_scale_f32_32x32x64_f8f6f4 v[20:35], v[116:123], v[218:225], v[20:35], v162, v162 op_sel_hi:[0,0,0]
	s_nop 5
	v_max_f32_e32 v116, v85, v85
	v_max_f32_e32 v117, v84, v84
	v_max_f32_e32 v116, v117, v116
	v_max3_f32 v116, v116, v86, v87
	v_max3_f32 v116, v116, v88, v89
	v_max3_f32 v116, v116, v90, v91
	v_max3_f32 v116, v116, v92, v93
	v_max3_f32 v116, v116, v94, v95
	v_max3_f32 v116, v116, v96, v97
	v_max3_f32 v116, v116, v98, v99
	v_max3_f32 v116, v116, v68, v69
	v_max3_f32 v116, v116, v70, v71
	v_max3_f32 v116, v116, v72, v73
	v_max3_f32 v116, v116, v74, v75
	v_max3_f32 v116, v116, v76, v77
	v_max3_f32 v116, v116, v78, v79
	v_max3_f32 v116, v116, v80, v81
	v_max3_f32 v116, v116, v82, v83
	v_mov_b32_e32 v117, v116
	s_nop 1
	v_permlane32_swap_b32_e32 v116, v117
	v_max_f32_e32 v117, v117, v117
	v_max_f32_e32 v116, v116, v116
	v_max_f32_e32 v116, v116, v117
	v_sub_f32_e32 v117, v116, v185
	v_cmp_ge_f32_e32 vcc, s81, v117
	v_max_f32_e32 v117, v185, v185
	v_max_f32_e32 v116, v117, v116
	v_sub_f32_e32 v117, v185, v116
	v_mul_f32_e32 v117, 0x3e0293ee, v117
	v_exp_f32_e32 v117, v117
	s_cmp_eq_u64 vcc, exec
	s_cselect_b64 s[6:7], -1, 0
	s_waitcnt vmcnt(2)
	s_lshl_b32 s38, s71, 13
	v_cndmask_b32_e64 v133, v117, 1.0, s[6:7]
	v_add_u32_e32 v117, s38, v178
	s_waitcnt vmcnt(1)
	ds_write_b128 v117, v[148:151]
	v_add_u32_e32 v117, s38, v177
	v_cmp_gt_f32_e32 vcc, 1.0, v133
	s_waitcnt vmcnt(0)
	ds_write_b128 v117, v[152:155] offset:24576
	s_cbranch_vccz .LBB0_2670
	s_and_saveexec_b64 s[18:19], s[4:5]
	ds_write_b32 v170, v133 offset:49280
	s_or_b64 exec, exec, s[18:19]
	v_add_u32_e32 v117, v157, v169
	s_waitcnt lgkmcnt(0)
	v_add_u32_e32 v126, 0xc080, v117
	v_add_u32_e32 v128, 0xc088, v117
	v_add_u32_e32 v130, 0xc0a0, v117
	v_add_u32_e32 v118, 0xc0c0, v117
	v_add_u32_e32 v120, 0xc0c8, v117
	v_add_u32_e32 v122, 0xc0e0, v117
	v_add_u32_e32 v132, 0xc0a8, v117
	v_add_u32_e32 v117, 0xc0e8, v117
	ds_read2_b32 v[118:119], v118 offset1:1
	ds_read2_b32 v[120:121], v120 offset1:1
	ds_read2_b32 v[122:123], v122 offset1:1
	ds_read2_b32 v[124:125], v117 offset1:1
	ds_read2_b32 v[126:127], v126 offset1:1
	ds_read2_b32 v[128:129], v128 offset1:1
	ds_read2_b32 v[130:131], v130 offset1:1
	ds_read2_b32 v[134:135], v132 offset1:1
	s_waitcnt lgkmcnt(4)
	v_pk_mul_f32 v[18:19], v[18:19], v[124:125]
	v_pk_mul_f32 v[16:17], v[16:17], v[122:123]
	v_pk_mul_f32 v[14:15], v[14:15], v[120:121]
	v_pk_mul_f32 v[12:13], v[12:13], v[118:119]
	s_waitcnt lgkmcnt(0)
	v_pk_mul_f32 v[10:11], v[10:11], v[134:135]
	v_pk_mul_f32 v[8:9], v[8:9], v[130:131]
	v_pk_mul_f32 v[6:7], v[6:7], v[128:129]
	v_pk_mul_f32 v[4:5], v[4:5], v[126:127]
	v_pk_mul_f32 v[66:67], v[66:67], v[124:125]
	v_pk_mul_f32 v[64:65], v[64:65], v[122:123]
	v_pk_mul_f32 v[62:63], v[62:63], v[120:121]
	v_pk_mul_f32 v[60:61], v[60:61], v[118:119]
	v_pk_mul_f32 v[58:59], v[58:59], v[134:135]
	v_pk_mul_f32 v[56:57], v[56:57], v[130:131]
	v_pk_mul_f32 v[54:55], v[54:55], v[128:129]
	v_pk_mul_f32 v[52:53], v[52:53], v[126:127]
	v_pk_mul_f32 v[50:51], v[50:51], v[124:125]
	v_pk_mul_f32 v[48:49], v[48:49], v[122:123]
	v_pk_mul_f32 v[46:47], v[46:47], v[120:121]
	v_pk_mul_f32 v[44:45], v[44:45], v[118:119]
	v_pk_mul_f32 v[42:43], v[42:43], v[134:135]
	v_pk_mul_f32 v[40:41], v[40:41], v[130:131]
	v_pk_mul_f32 v[38:39], v[38:39], v[128:129]
	v_pk_mul_f32 v[36:37], v[36:37], v[126:127]
	v_pk_mul_f32 v[34:35], v[34:35], v[124:125]
	v_pk_mul_f32 v[32:33], v[32:33], v[122:123]
	v_pk_mul_f32 v[30:31], v[30:31], v[120:121]
	v_pk_mul_f32 v[28:29], v[28:29], v[118:119]
	v_pk_mul_f32 v[26:27], v[26:27], v[134:135]
	v_pk_mul_f32 v[24:25], v[24:25], v[130:131]
	v_pk_mul_f32 v[22:23], v[22:23], v[128:129]
	v_pk_mul_f32 v[20:21], v[20:21], v[126:127]

.LBB0_2806:
	s_load_dwordx4 s[68:71], s[0:1], 0xc0
	v_readlane_b32 s48, v255, 3
	s_or_b32 s16, s48, 6
	s_waitcnt lgkmcnt(0)
	s_cmp_ge_i32 s16, s71
	s_cbranch_scc1 .LBB0_2818
	v_readlane_b32 s4, v253, 2
	s_mov_b32 s20, s91
	v_readlane_b32 s5, v253, 3
	v_readlane_b32 s21, v253, 4
	v_mov_b32_e32 v2, s21
	ds_read_b32 v2, v2 offset:8
	s_waitcnt lgkmcnt(0)
	v_readfirstlane_b32 s22, v2
	s_cmp_eq_u32 s22, 2
	s_cbranch_scc0 .Lorig_pb3
	s_waitcnt vmcnt(0)
	s_barrier
	v_readlane_b32 s58, v253, 5
	s_mov_b32 s66, s76
	v_cmp_eq_u32_e32 vcc, 0, v0
	s_and_saveexec_b64 s[2:3], vcc
	s_cbranch_execz .LBB0_2860
	s_lshl_b32 s10, s20, 8
	s_add_u32 s12, s4, s10
	s_addc_u32 s13, s5, 0
	s_add_u32 s12, s12, 0x3700
	s_addc_u32 s13, s13, 0
	s_add_u32 s8, s12, 0x1000
	s_addc_u32 s9, s13, 0
	v_mov_b32_e32 v4, 1
	global_atomic_add v4, v3, v4, s[12:13] sc0
	buffer_inv sc1
	s_waitcnt vmcnt(0)
	v_and_b32_e32 v5, 31, v4
	v_lshrrev_b32_e32 v2, 5, v4
	v_cmp_eq_u32_e32 vcc, 31, v5
	s_cbranch_vccz .Lloc3_spin
	global_atomic_add v3, v251, s[8:9]
	s_branch .Lloc3_acq

.Lloc3_poll:
	global_load_dword v4, v3, s[8:9] sc1
	s_waitcnt vmcnt(0)
	v_cmp_ne_u32_e32 vcc, v4, v2
	s_cbranch_vccnz .Lloc3_acq
	s_sleep 4
	s_add_i32 s22, s22, 1
	s_cmp_lt_u32 s22, 0x40000
	s_cbranch_scc1 .Lloc3_poll
.Lloc3_acq:
	s_waitcnt vmcnt(0)
	s_branch .LBB0_2860
.Lorig_pb3:
	s_waitcnt vmcnt(0)
	v_mov_b32_e32 v2, v0
	s_waitcnt vmcnt(0)
	s_barrier
	s_nop 0
	v_cmp_eq_u32_e32 vcc, 0, v2
	s_and_saveexec_b64 s[2:3], vcc
	v_readlane_b32 s58, v253, 5
	s_mov_b32 s66, s76
	s_cbranch_execz .LBB0_2860
	v_mov_b32_e32 v2, s21
	s_waitcnt vmcnt(0) expcnt(0) lgkmcnt(0)
	ds_read_b32 v5, v2
	ds_read_b32 v4, v2 offset:4
	s_waitcnt lgkmcnt(1)
	v_cmp_ne_u32_e32 vcc, 0, v5
	s_cbranch_vccnz .LBB0_2824
	v_readlane_b32 s6, v253, 0
	v_readlane_b32 s7, v253, 1
	s_load_dwordx2 s[10:11], s[6:7], 0x4
	s_add_u32 s6, s4, 0x1000
	s_addc_u32 s7, s5, 0
	s_add_u32 s8, s4, 0x1100
	s_addc_u32 s9, s5, 0
	s_waitcnt lgkmcnt(0)
	s_mul_i32 s22, s10, s88
	s_add_u32 s10, s4, 0x1200
	s_mul_i32 s22, s22, s11
	s_addc_u32 s11, s5, 0
	s_add_u32 s12, s4, 0x1300
	s_addc_u32 s13, s5, 0
	s_mov_b32 s23, 1
	s_branch .LBB0_2811

.LBB0_3025:
	s_or_b64 exec, exec, s[8:9]
	buffer_inv sc1
	s_waitcnt vmcnt(0)
	v_readfirstlane_b32 s6, v4
	s_mov_b32 s7, s36
	s_nop 0
	v_add_u32_e32 v2, s6, v2
	s_add_i32 s6, s10, 0x11c0
	s_lshl_b64 s[6:7], s[6:7], 2
	s_add_u32 s8, s2, s6
	v_and_b32_e32 v4, 31, v2
	s_addc_u32 s9, s3, s7
	v_cmp_ne_u32_e32 vcc, 31, v4
	s_mov_b64 s[10:11], -1
	v_mov_b64_e32 v[4:5], s[8:9]
	s_and_saveexec_b64 s[6:7], vcc
	s_cbranch_execz .LBB0_3037
	global_load_dword v4, v3, s[8:9] sc1
	v_lshrrev_b32_e32 v2, 5, v2
	s_mov_b64 s[14:15], 0
	s_waitcnt vmcnt(0)
	v_cmp_eq_u32_e32 vcc, v4, v2
	s_and_saveexec_b64 s[12:13], vcc
	s_cbranch_execz .LBB0_3036
	s_add_u32 s10, s2, 0x200
	s_addc_u32 s11, s3, 0
	s_mov_b32 s22, 1
	s_branch .LBB0_3029

.LBB0_3039:
	s_or_b64 exec, exec, s[6:7]
	s_waitcnt vmcnt(0)
	s_waitcnt vmcnt(0)

.LBB0_3123:
	s_add_i32 s16, s48, 9
	s_waitcnt lgkmcnt(0)
	s_cmp_ge_i32 s16, s71
	s_cbranch_scc1 .LBB0_3177
	v_readlane_b32 s4, v253, 2
	v_readlane_b32 s21, v253, 4
	s_mov_b32 s20, s91
	v_readlane_b32 s5, v253, 3
	v_mov_b32_e32 v2, s21
	ds_read_b32 v2, v2 offset:8
	s_waitcnt lgkmcnt(0)
	v_readfirstlane_b32 s22, v2
	s_cmp_eq_u32 s22, 2
	s_cbranch_scc0 .Lorig_pb6
	s_waitcnt vmcnt(0)
	s_barrier
	v_cmp_eq_u32_e32 vcc, 0, v0
	s_and_saveexec_b64 s[2:3], vcc
	s_cbranch_execz .LBB0_3176
	s_lshl_b32 s10, s20, 8
	s_add_u32 s12, s4, s10
	s_addc_u32 s13, s5, 0
	s_add_u32 s12, s12, 0x3700
	s_addc_u32 s13, s13, 0
	s_add_u32 s8, s12, 0x1000
	s_addc_u32 s9, s13, 0
	v_mov_b32_e32 v4, 1
	global_atomic_add v4, v3, v4, s[12:13] sc0
	buffer_inv sc1
	s_waitcnt vmcnt(0)
	v_and_b32_e32 v5, 31, v4
	v_lshrrev_b32_e32 v2, 5, v4
	v_cmp_eq_u32_e32 vcc, 31, v5
	s_cbranch_vccz .Lloc6_spin
	global_atomic_add v3, v251, s[8:9]
	s_branch .Lloc6_acq

.LBB0_3205:
	v_readlane_b32 s2, v253, 2
	v_readlane_b32 s3, v253, 3
	v_readlane_b32 s20, v253, 4
	s_mov_b32 s16, s91
	v_mov_b32_e32 v2, s20
	ds_read_b32 v2, v2 offset:8
	s_waitcnt lgkmcnt(0)
	v_readfirstlane_b32 s22, v2
	s_cmp_eq_u32 s22, 2
	s_cbranch_scc0 .Lorig_pb7
	s_waitcnt vmcnt(0)
	s_barrier
	v_cmp_eq_u32_e32 vcc, 0, v0
	s_and_saveexec_b64 s[4:5], vcc
	s_cbranch_execz .Lto_897
	s_lshl_b32 s10, s16, 8
	s_add_u32 s12, s2, s10
	s_addc_u32 s13, s3, 0
	s_add_u32 s12, s12, 0x3700
	s_addc_u32 s13, s13, 0
	s_add_u32 s8, s12, 0x1000
	s_addc_u32 s9, s13, 0
	v_mov_b32_e32 v4, 1
	global_atomic_add v4, v3, v4, s[12:13] sc0
	buffer_inv sc1
	s_waitcnt vmcnt(0)
	v_and_b32_e32 v5, 31, v4
	v_lshrrev_b32_e32 v2, 5, v4
	v_cmp_eq_u32_e32 vcc, 31, v5
	s_cbranch_vccz .Lloc7_spin
	global_atomic_add v3, v251, s[8:9]
	s_branch .Lloc7_acq

	.amdhsa_kernel _Z6mk_fwd4Args
		.amdhsa_group_segment_fixed_size 0
		.amdhsa_private_segment_fixed_size 0
		.amdhsa_kernarg_size 464
		.amdhsa_user_sgpr_count 2
		.amdhsa_user_sgpr_dispatch_ptr 0
		.amdhsa_user_sgpr_queue_ptr 0
		.amdhsa_user_sgpr_kernarg_segment_ptr 1
		.amdhsa_user_sgpr_dispatch_id 0
		.amdhsa_user_sgpr_kernarg_preload_length 0
		.amdhsa_user_sgpr_kernarg_preload_offset 0
		.amdhsa_user_sgpr_private_segment_size 0
		.amdhsa_uses_dynamic_stack 0
		.amdhsa_enable_private_segment 0
		.amdhsa_system_sgpr_workgroup_id_x 1
		.amdhsa_system_sgpr_workgroup_id_y 0
		.amdhsa_system_sgpr_workgroup_id_z 0
		.amdhsa_system_sgpr_workgroup_info 0
		.amdhsa_system_vgpr_workitem_id 0
		.amdhsa_next_free_vgpr 256
		.amdhsa_next_free_sgpr 102
		.amdhsa_accum_offset 256
		.amdhsa_reserve_vcc 1
		.amdhsa_float_round_mode_32 0
		.amdhsa_float_round_mode_16_64 0
		.amdhsa_float_denorm_mode_32 3
		.amdhsa_float_denorm_mode_16_64 3
		.amdhsa_dx10_clamp 1
		.amdhsa_ieee_mode 1
		.amdhsa_fp16_overflow 0
		.amdhsa_tg_split 0
		.amdhsa_exception_fp_ieee_invalid_op 0
		.amdhsa_exception_fp_denorm_src 0
		.amdhsa_exception_fp_ieee_div_zero 0
		.amdhsa_exception_fp_ieee_overflow 0
		.amdhsa_exception_fp_ieee_underflow 0
		.amdhsa_exception_fp_ieee_inexact 0
		.amdhsa_exception_int_div_zero 0
	.end_amdhsa_kernel

amdhsa.kernels:
  - .agpr_count:     0
    .args:
      - .offset:         0
        .size:           208
        .value_kind:     by_value
      - .offset:         208
        .size:           4
        .value_kind:     hidden_block_count_x
      - .offset:         212
        .size:           4
        .value_kind:     hidden_block_count_y
      - .offset:         216
        .size:           4
        .value_kind:     hidden_block_count_z
      - .offset:         220
        .size:           2
        .value_kind:     hidden_group_size_x
      - .offset:         222
        .size:           2
        .value_kind:     hidden_group_size_y
      - .offset:         224
        .size:           2
        .value_kind:     hidden_group_size_z
      - .offset:         226
        .size:           2
        .value_kind:     hidden_remainder_x
      - .offset:         228
        .size:           2
        .value_kind:     hidden_remainder_y
      - .offset:         230
        .size:           2
        .value_kind:     hidden_remainder_z
      - .offset:         248
        .size:           8
        .value_kind:     hidden_global_offset_x
      - .offset:         256
        .size:           8
        .value_kind:     hidden_global_offset_y
      - .offset:         264
        .size:           8
        .value_kind:     hidden_global_offset_z
      - .offset:         272
        .size:           2
        .value_kind:     hidden_grid_dims
      - .offset:         328
        .size:           4
        .value_kind:     hidden_dynamic_lds_size
    .group_segment_fixed_size: 0
    .kernarg_segment_align: 8
    .kernarg_segment_size: 464
    .language:       OpenCL C
    .language_version:
      - 2
      - 0
    .max_flat_workgroup_size: 512
    .name:           _Z6mk_fwd4Args
    .private_segment_fixed_size: 0
    .sgpr_count:     108
    .sgpr_spill_count: 212
    .symbol:         _Z6mk_fwd4Args.kd
    .uniform_work_group_size: 1
    .uses_dynamic_stack: false
    .vgpr_count:     256
    .vgpr_spill_count: 0
    .wavefront_size: 64
